# attention drain check (scan workgroups look first) + P4 weight share first in two classes
# speedup vs baseline: 1.0028x; 1.0028x over previous
; __device__ __forceinline__ int lane_id() { int l; asm volatile("v_mbcnt_lo_u32_b32 %0, -1, 0\n\tv_mbcnt_hi_u32_b32 %0, -1, %0" : "=v"(l)); return l; }
; #define LOAD_P() Params p; { const __attribute__((address_space(4))) Params* q_ = (const __attribute__((address_space(4))) Params*)__builtin_amdgcn_kernarg_segment_ptr(); asm volatile("" : "+s"(q_)); \
;     p = *q_; p.wave_id = wave_id; } unsigned char* ws = p.ws; (void)ws
; __global__ void __launch_bounds__(NTHREADS, 2) mega_fwd(Params p_in) {
;     ...
;     { LOAD_P();
;       if (bx < 2 * BATCH * NHEAD) {
;         if (wave_id == 0 && lane_id() == 0) { unsigned* pc = (unsigned*)(ws + WS_PREPCTR); while (__hip_atomic_load(pc, __ATOMIC_RELAXED, __HIP_MEMORY_SCOPE_AGENT) < (unsigned)nb) __builtin_amdgcn_s_sleep(2); }
;         asm volatile("" ::: "memory"); __syncthreads();
;         hgrn_scan(p, lds, bx); }
.LBB0_390:
	s_mov_b32 s101, 0
	s_mov_b64 s[4:5], s[0:1]
	s_load_dwordx2 s[28:29], s[4:5], 0x68
	s_load_dwordx4 s[24:27], s[4:5], 0xb0
	s_cmp_gt_i32 s2, 63
	s_cbranch_scc1 .Lw2_first
	s_and_b64 vcc, exec, s[94:95]
	s_cbranch_vccnz .LBB0_397
	s_waitcnt vmcnt(4)
	v_mbcnt_lo_u32_b32 v0, -1, 0
	v_mbcnt_hi_u32_b32 v0, -1, v0
	s_nop 0
	v_cmp_eq_u32_e32 vcc, 0, v0
	s_and_saveexec_b64 s[4:5], vcc
	s_cbranch_execz .LBB0_396
	v_mov_b32_e32 v0, 0x9000
	s_waitcnt lgkmcnt(0)
	global_load_dword v0, v0, s[26:27] offset:2048 sc1
	s_add_u32 s6, s26, 0x9800
	s_addc_u32 s7, s27, 0
	s_waitcnt vmcnt(0)
	v_cmp_le_u32_e32 vcc, s33, v0
	s_cbranch_vccnz .LBB0_396
	v_mov_b32_e32 v0, 0

; __global__ void __launch_bounds__(NTHREADS, 2) mega_fwd(Params p_in) {
;     ...
;         hgrn_scan(p, lds, bx); }
;       __syncthreads();
.LBB0_435:
	s_mov_b32 s101, 1
	s_waitcnt lgkmcnt(0)
	s_barrier

; #define LAS __attribute__((address_space(3)))
; __device__ __forceinline__ void phase_attn(const Params& p, LAS unsigned char* lds) {
;     ...
;         if (tid == 0) { unsigned v = 0xffffffffu;
;             while (qoff < 8) { const int qx = (myx + qoff) & 7; const unsigned n = atomicAdd(ctr + 64 * qx, 1u); if (n < 64u) { v = (unsigned)((qx + 8 * (n >> 4)) * 16 + (n & 15)); break; } ++qoff; }
;             *(LAS unsigned*)(lds + A_ITEM) = v; }
.LBB0_438:
	s_and_saveexec_b64 s[50:51], s[4:5]
	s_cbranch_execz .LBB0_448
	v_mov_b32_e32 v0, -1
	s_cmp_eq_u32 s101, 0
	s_cbranch_scc1 .Latt_claim
	s_mov_b32 s101, 0
	v_mov_b32_e32 v133, -1
	s_branch .Latt_bulk

; __device__ __forceinline__ void phase_attn(const Params& p, LAS unsigned char* lds) {
;     ...
;         if (tid == 0) { unsigned v = 0xffffffffu;
;             while (qoff < 8) { const int qx = (myx + qoff) & 7; const unsigned n = atomicAdd(ctr + 64 * qx, 1u); if (n < 64u) { v = (unsigned)((qx + 8 * (n >> 4)) * 16 + (n & 15)); break; } ++qoff; }
.Latt_bulk:
	s_add_i32 s96, s43, 0
	s_and_b32 s96, s96, 7
	s_lshl_b32 s96, s96, 8
	v_mov_b32_e32 v2, s96
	global_load_dword v171, v2, s[26:27] sc1
	s_add_i32 s96, s43, 1
	s_and_b32 s96, s96, 7
	s_lshl_b32 s96, s96, 8
	v_mov_b32_e32 v2, s96
	global_load_dword v172, v2, s[26:27] sc1
	s_add_i32 s96, s43, 2
	s_and_b32 s96, s96, 7
	s_lshl_b32 s96, s96, 8
	v_mov_b32_e32 v2, s96
	global_load_dword v173, v2, s[26:27] sc1
	s_add_i32 s96, s43, 3
	s_and_b32 s96, s96, 7
	s_lshl_b32 s96, s96, 8
	v_mov_b32_e32 v2, s96
	global_load_dword v174, v2, s[26:27] sc1
	s_add_i32 s96, s43, 4
	s_and_b32 s96, s96, 7
	s_lshl_b32 s96, s96, 8
	v_mov_b32_e32 v2, s96
	global_load_dword v175, v2, s[26:27] sc1
	s_add_i32 s96, s43, 5
	s_and_b32 s96, s96, 7
	s_lshl_b32 s96, s96, 8
	v_mov_b32_e32 v2, s96
	global_load_dword v176, v2, s[26:27] sc1
	s_add_i32 s96, s43, 6
	s_and_b32 s96, s96, 7
	s_lshl_b32 s96, s96, 8
	v_mov_b32_e32 v2, s96
	global_load_dword v177, v2, s[26:27] sc1
	s_add_i32 s96, s43, 7
	s_and_b32 s96, s96, 7
	s_lshl_b32 s96, s96, 8
	v_mov_b32_e32 v2, s96
	global_load_dword v178, v2, s[26:27] sc1
	s_waitcnt vmcnt(0)
	s_mov_b32 s97, 0
	v_cmp_le_u32_e32 vcc, 64, v171
	s_and_b32 s96, vcc_lo, 1
	s_or_b32 s97, s97, s96
	v_cmp_le_u32_e32 vcc, 64, v172
	s_and_b32 s96, vcc_lo, 1
	s_lshl_b32 s96, s96, 1
	s_or_b32 s97, s97, s96
	v_cmp_le_u32_e32 vcc, 64, v173
	s_and_b32 s96, vcc_lo, 1
	s_lshl_b32 s96, s96, 2
	s_or_b32 s97, s97, s96
	v_cmp_le_u32_e32 vcc, 64, v174
	s_and_b32 s96, vcc_lo, 1
	s_lshl_b32 s96, s96, 3
	s_or_b32 s97, s97, s96
	v_cmp_le_u32_e32 vcc, 64, v175
	s_and_b32 s96, vcc_lo, 1
	s_lshl_b32 s96, s96, 4
	s_or_b32 s97, s97, s96
	v_cmp_le_u32_e32 vcc, 64, v176
	s_and_b32 s96, vcc_lo, 1
	s_lshl_b32 s96, s96, 5
	s_or_b32 s97, s97, s96
	v_cmp_le_u32_e32 vcc, 64, v177
	s_and_b32 s96, vcc_lo, 1
	s_lshl_b32 s96, s96, 6
	s_or_b32 s97, s97, s96
	v_cmp_le_u32_e32 vcc, 64, v178
	s_and_b32 s96, vcc_lo, 1
	s_lshl_b32 s96, s96, 7
	s_or_b32 s97, s97, s96
	v_readfirstlane_b32 s98, v133
	s_add_i32 s98, s98, 1
